# grid barrier: non-leader workgroups wait on the top-level generation word directly (two hand-offs fewer per barrier)
# speedup vs baseline: 1.0107x; 1.0033x over previous
.LBB0_489:
	s_or_b64 exec, exec, s[6:7]
	v_cvt_f32_u32_e32 v5, v3
	s_waitcnt vmcnt(0)
	v_readfirstlane_b32 s4, v4
	v_sub_u32_e32 v4, 0, v3
	v_rcp_iflag_f32_e32 v5, v5
	v_add_u32_e32 v6, s4, v0
	v_mul_f32_e32 v5, 0x4f7ffffe, v5
	v_cvt_u32_f32_e32 v5, v5
	v_mul_lo_u32 v0, v4, v5
	v_mul_hi_u32 v0, v5, v0
	v_add_u32_e32 v0, v5, v0
	v_mul_hi_u32 v0, v6, v0
	v_mul_lo_u32 v4, v0, v3
	v_sub_u32_e32 v4, v6, v4
	v_add_u32_e32 v5, 1, v0
	v_cmp_ge_u32_e32 vcc, v4, v3
	s_nop 1
	v_cndmask_b32_e32 v0, v0, v5, vcc
	v_sub_u32_e32 v5, v4, v3
	v_cndmask_b32_e32 v4, v4, v5, vcc
	v_add_u32_e32 v5, 1, v0
	v_cmp_ge_u32_e32 vcc, v4, v3
	v_add_u32_e32 v4, 1, v6
	s_nop 0
	v_cndmask_b32_e32 v0, v0, v5, vcc
	v_mul_lo_u32 v5, v3, v0
	v_add_u32_e32 v3, v5, v3
	v_cmp_ne_u32_e32 vcc, v4, v3
	s_and_saveexec_b64 s[4:5], vcc
	s_xor_b64 s[4:5], exec, s[4:5]
	s_cbranch_execz .LBB0_503
	s_waitcnt lgkmcnt(0)
	v_readlane_b32 s8, v241, 25
	v_readlane_b32 s9, v241, 26
	s_nop 4
	global_load_dword v2, v1, s[8:9] sc1
	s_waitcnt vmcnt(0)
	v_cmp_eq_u32_e32 vcc, v2, v0
	s_and_saveexec_b64 s[6:7], vcc
	s_cbranch_execz .LBB0_502
	s_mov_b32 s24, 1
	s_mov_b64 s[10:11], 0
	s_branch .LBB0_493
